# adds: nt cache policy on the attention-merge output stores
# speedup vs baseline: 1.0133x; 1.0028x over previous
; DI float frcp(float x) { return __builtin_amdgcn_rcpf(x); }
; DI void merge_phase(bf16_t* QKV, const float* LSE, int G, int bid) {
;     ...
;     for (int tl0 = gw; tl0 < TH; tl0 += 4 * NGW) {
;         u32x4 a[4][2], b[4][2], c[4][2]; float l0[4], l1[4], l2[4]; bf16_t* p0[4];
; #pragma unroll
;         for (int r = 0; r < 4; ++r) { const int tl = tl0 + r * NGW; const int bl = tl >> 13, t = tl & 8191;
;             const int pr0 = tl, pr1 = (bl << 13) + ((t & 3) << 11) + (t >> 2), pr2 = (bl << 13) + ((t & 15) << 9) + (t >> 4);
;             l0[r] = LSE[((size_t)0 * TH + pr0) * 16 + h]; l1[r] = LSE[((size_t)1 * TH + pr1) * 16 + h]; l2[r] = LSE[((size_t)2 * TH + pr2) * 16 + h];
;             p0[r] = QKV + (size_t)pr0 * 1024 + col; const bf16_t* p1 = QKV + SEC + (size_t)pr1 * 1024 + col; const bf16_t* p2 = QKV + 2 * SEC + (size_t)pr2 * 1024 + col;
; #pragma unroll
;             for (int q = 0; q < 2; ++q) { a[r][q] = *(const u32x4*)(p0[r] + 8 * q); b[r][q] = *(const u32x4*)(p1 + 8 * q); c[r][q] = *(const u32x4*)(p2 + 8 * q); } }
; #pragma unroll
;         for (int r = 0; r < 4; ++r) {
;             const float m = fmaxf(l0[r], fmaxf(l1[r], l2[r])); float w0 = __expf(l0[r] - m), w1 = __expf(l1[r] - m), w2 = __expf(l2[r] - m); const float is = frcp(w0 + w1 + w2); w0 *= is; w1 *= is; w2 *= is;
.LBB0_308:
	v_and_b32_e32 v74, 0x1800, v117
	v_and_b32_e32 v1, 0xffffe000, v72
	v_bfe_u32 v0, v72, 2, 11
	v_ashrrev_i32_e32 v73, 31, v72
	v_or3_b32 v0, v0, v1, v74
	v_and_b32_e32 v49, 0x1e00, v116
	v_bfe_u32 v2, v72, 4, 9
	v_lshlrev_b64 v[4:5], 6, v[72:73]
	v_or3_b32 v2, v1, v2, v49
	v_lshl_add_u64 v[4:5], v[96:97], 0, v[4:5]
	v_ashrrev_i32_e32 v1, 31, v0
	global_load_dword v118, v[4:5], off
	v_lshlrev_b64 v[4:5], 6, v[0:1]
	v_lshl_add_u64 v[4:5], s[20:21], 0, v[4:5]
	v_lshl_add_u64 v[4:5], v[4:5], 0, v[112:113]
	v_add_co_u32_e32 v4, vcc, s41, v4
	v_ashrrev_i32_e32 v3, 31, v2
	s_nop 0
	v_addc_co_u32_e32 v5, vcc, 0, v5, vcc
	global_load_dword v119, v[4:5], off
	v_lshlrev_b64 v[4:5], 6, v[2:3]
	v_lshl_add_u64 v[4:5], s[20:21], 0, v[4:5]
	v_lshl_add_u64 v[4:5], v[4:5], 0, v[112:113]
	v_add_co_u32_e32 v4, vcc, s42, v4
	v_add_u32_e32 v104, s33, v72
	s_nop 0
	v_addc_co_u32_e32 v5, vcc, 0, v5, vcc
	global_load_dword v120, v[4:5], off
	v_lshlrev_b64 v[4:5], 11, v[72:73]
	v_lshlrev_b64 v[0:1], 11, v[0:1]
	v_lshlrev_b64 v[2:3], 11, v[2:3]
	v_ashrrev_i32_e32 v105, 31, v104
	v_lshl_add_u64 v[106:107], v[98:99], 0, v[4:5]
	v_lshl_add_u64 v[0:1], v[100:101], 0, v[0:1]
	v_lshl_add_u64 v[12:13], v[102:103], 0, v[2:3]
	v_lshlrev_b64 v[28:29], 6, v[104:105]
	global_load_dwordx4 v[4:7], v[106:107], off offset:16
	global_load_dwordx4 v[16:19], v[106:107], off
	global_load_dwordx4 v[8:11], v[0:1], off offset:16
	global_load_dwordx4 v[20:23], v[0:1], off
	s_nop 0
	global_load_dwordx4 v[0:3], v[12:13], off offset:16
	s_nop 0
	global_load_dwordx4 v[12:15], v[12:13], off
	v_lshl_add_u64 v[28:29], v[96:97], 0, v[28:29]
	global_load_dword v121, v[28:29], off
	v_and_b32_e32 v25, 0xffffe000, v104
	v_bfe_u32 v24, v104, 2, 11
	v_add_u32_e32 v26, s99, v116
	v_or3_b32 v24, v74, v24, v25
	v_and_b32_e32 v26, 0x1e00, v26
	v_bfe_u32 v27, v104, 4, 9
	v_or3_b32 v26, v26, v27, v25
	v_ashrrev_i32_e32 v25, 31, v24
	v_lshlrev_b64 v[28:29], 6, v[24:25]
	v_lshl_add_u64 v[28:29], s[20:21], 0, v[28:29]
	v_lshl_add_u64 v[28:29], v[28:29], 0, v[112:113]
	v_add_co_u32_e32 v28, vcc, s41, v28
	v_ashrrev_i32_e32 v27, 31, v26
	s_nop 0
	v_addc_co_u32_e32 v29, vcc, 0, v29, vcc
	global_load_dword v128, v[28:29], off
	v_lshlrev_b64 v[28:29], 6, v[26:27]
	v_lshl_add_u64 v[28:29], s[20:21], 0, v[28:29]
	v_lshl_add_u64 v[28:29], v[28:29], 0, v[112:113]
	v_add_co_u32_e32 v28, vcc, s42, v28
	v_lshlrev_b64 v[24:25], 11, v[24:25]
	s_nop 0
	v_addc_co_u32_e32 v29, vcc, 0, v29, vcc
	global_load_dword v129, v[28:29], off
	v_lshlrev_b64 v[28:29], 11, v[104:105]
	v_lshlrev_b64 v[26:27], 11, v[26:27]
	v_lshl_add_u64 v[108:109], v[98:99], 0, v[28:29]
	v_lshl_add_u64 v[24:25], v[100:101], 0, v[24:25]
	v_lshl_add_u64 v[36:37], v[102:103], 0, v[26:27]
	global_load_dwordx4 v[28:31], v[108:109], off offset:16
	global_load_dwordx4 v[40:43], v[108:109], off
	global_load_dwordx4 v[32:35], v[24:25], off offset:16
	global_load_dwordx4 v[44:47], v[24:25], off
	s_nop 0
	global_load_dwordx4 v[24:27], v[36:37], off offset:16
	s_nop 0
	global_load_dwordx4 v[36:39], v[36:37], off
	v_add_u32_e32 v48, s98, v72
	v_and_b32_e32 v51, 0xffffe000, v48
	v_bfe_u32 v52, v48, 4, 9
	v_bfe_u32 v50, v48, 2, 11
	v_or3_b32 v52, v49, v52, v51
	v_ashrrev_i32_e32 v49, 31, v48
	v_or3_b32 v50, v74, v50, v51
	v_lshlrev_b64 v[54:55], 6, v[48:49]
	v_lshl_add_u64 v[54:55], v[96:97], 0, v[54:55]
	v_ashrrev_i32_e32 v51, 31, v50
	global_load_dword v105, v[54:55], off
	v_lshlrev_b64 v[54:55], 6, v[50:51]
	v_lshl_add_u64 v[54:55], s[20:21], 0, v[54:55]
	v_lshl_add_u64 v[54:55], v[54:55], 0, v[112:113]
	v_add_co_u32_e32 v54, vcc, s41, v54
	v_ashrrev_i32_e32 v53, 31, v52
	s_nop 0
	v_addc_co_u32_e32 v55, vcc, 0, v55, vcc
	global_load_dword v130, v[54:55], off
	v_lshlrev_b64 v[54:55], 6, v[52:53]
	v_lshl_add_u64 v[54:55], s[20:21], 0, v[54:55]
	v_lshl_add_u64 v[54:55], v[54:55], 0, v[112:113]
	v_add_co_u32_e32 v54, vcc, s42, v54
	v_add_u32_e32 v72, s40, v72
	s_nop 0
	v_addc_co_u32_e32 v55, vcc, 0, v55, vcc
	global_load_dword v131, v[54:55], off
	v_and_b32_e32 v73, 0xffffe000, v72
	v_bfe_u32 v75, v72, 2, 11
	s_mul_i32 s2, s3, 0x3000
	v_or3_b32 v74, v74, v75, v73
	v_add_u32_e32 v75, s2, v116
	v_and_b32_e32 v75, 0x1e00, v75
	v_bfe_u32 v76, v72, 4, 9
	s_waitcnt vmcnt(18)
	v_max3_f32 v124, v118, v119, v120
	v_sub_f32_e32 v118, v118, v124
	v_mul_f32_e32 v118, 0x3fb8aa3b, v118
	v_exp_f32_e32 v123, v118
	v_sub_f32_e32 v118, v119, v124
	v_mul_f32_e32 v118, 0x3fb8aa3b, v118
	v_exp_f32_e32 v122, v118
	v_sub_f32_e32 v118, v120, v124
	v_mul_f32_e32 v118, 0x3fb8aa3b, v118
	v_exp_f32_e32 v119, v118
	v_add_f32_e32 v118, v123, v122
	s_waitcnt vmcnt(16)
	v_lshlrev_b32_e32 v124, 16, v16
	s_waitcnt vmcnt(14)
	v_and_b32_e32 v125, 0xffff0000, v20
	v_add_f32_e32 v118, v119, v118
	v_rcp_f32_e32 v118, v118
	s_waitcnt vmcnt(12)
	v_lshlrev_b32_e32 v126, 16, v12
	v_and_b32_e32 v127, 0xffff0000, v12
	v_lshlrev_b64 v[48:49], 11, v[48:49]
	v_mul_f32_e32 v120, v119, v118
	v_pk_mul_f32 v[118:119], v[122:123], v[118:119] op_sel_hi:[1,0]
	v_lshlrev_b32_e32 v122, 16, v20
	v_and_b32_e32 v123, 0xffff0000, v16
	v_pk_mul_f32 v[124:125], v[118:119], v[124:125] op_sel:[1,0] op_sel_hi:[0,1]
	v_pk_fma_f32 v[122:123], v[118:119], v[122:123], v[124:125]
	v_or3_b32 v76, v75, v76, v73
	v_ashrrev_i32_e32 v73, 31, v72
	s_waitcnt vmcnt(11)
; DI unsigned pk2(float lo, float hi) { f32x2n v = {lo, hi}; bf16x2n b = __builtin_convertvector(v, bf16x2n); return __builtin_bit_cast(unsigned, b); }
; DI float frcp(float x) { return __builtin_amdgcn_rcpf(x); }
; DI void merge_phase(bf16_t* QKV, const float* LSE, int G, int bid) {
;     ...
;         for (int r = 0; r < 4; ++r) { const int tl = tl0 + r * NGW; const int bl = tl >> 13, t = tl & 8191;
;             const int pr0 = tl, pr1 = (bl << 13) + ((t & 3) << 11) + (t >> 2), pr2 = (bl << 13) + ((t & 15) << 9) + (t >> 4);
;             l0[r] = LSE[((size_t)0 * TH + pr0) * 16 + h]; l1[r] = LSE[((size_t)1 * TH + pr1) * 16 + h]; l2[r] = LSE[((size_t)2 * TH + pr2) * 16 + h];
;             p0[r] = QKV + (size_t)pr0 * 1024 + col; const bf16_t* p1 = QKV + SEC + (size_t)pr1 * 1024 + col; const bf16_t* p2 = QKV + 2 * SEC + (size_t)pr2 * 1024 + col;
; #pragma unroll
;             for (int q = 0; q < 2; ++q) { a[r][q] = *(const u32x4*)(p0[r] + 8 * q); b[r][q] = *(const u32x4*)(p1 + 8 * q); c[r][q] = *(const u32x4*)(p2 + 8 * q); } }
; #pragma unroll
;         for (int r = 0; r < 4; ++r) {
;             const float m = fmaxf(l0[r], fmaxf(l1[r], l2[r])); float w0 = __expf(l0[r] - m), w1 = __expf(l1[r] - m), w2 = __expf(l2[r] - m); const float is = frcp(w0 + w1 + w2); w0 *= is; w1 *= is; w2 *= is;
; #pragma unroll
;             for (int q = 0; q < 2; ++q) { const u32x4 A = a[r][q], B = b[r][q], C = c[r][q]; u32x4 o;
;                 o.x = pk2(w0 * bflo(A.x) + w1 * bflo(B.x) + w2 * bflo(C.x), w0 * bfhi(A.x) + w1 * bfhi(B.x) + w2 * bfhi(C.x));
;                 o.y = pk2(w0 * bflo(A.y) + w1 * bflo(B.y) + w2 * bflo(C.y), w0 * bfhi(A.y) + w1 * bfhi(B.y) + w2 * bfhi(C.y));
;                 o.z = pk2(w0 * bflo(A.z) + w1 * bflo(B.z) + w2 * bflo(C.z), w0 * bfhi(A.z) + w1 * bfhi(B.z) + w2 * bfhi(C.z));
;                 o.w = pk2(w0 * bflo(A.w) + w1 * bflo(B.w) + w2 * bflo(C.w), w0 * bfhi(A.w) + w1 * bfhi(B.w) + w2 * bfhi(C.w));
;                 *(u32x4*)(p0[r] + 8 * q) = o; }
	v_pk_fma_f32 v[122:123], v[120:121], v[126:127], v[122:123] op_sel_hi:[0,1,1]
	v_lshl_add_u64 v[110:111], v[98:99], 0, v[48:49]
	v_lshlrev_b64 v[48:49], 11, v[50:51]
	v_lshlrev_b64 v[50:51], 11, v[52:53]
	v_lshlrev_b64 v[78:79], 6, v[72:73]
	v_cvt_pk_bf16_f32 v12, v122, v123
	v_and_b32_e32 v123, 0xffff0000, v17
	v_lshlrev_b32_e32 v16, 16, v17
	v_and_b32_e32 v17, 0xffff0000, v21
	v_lshl_add_u64 v[48:49], v[100:101], 0, v[48:49]
	v_lshl_add_u64 v[60:61], v[102:103], 0, v[50:51]
	v_lshl_add_u64 v[78:79], v[96:97], 0, v[78:79]
	v_ashrrev_i32_e32 v75, 31, v74
	v_lshlrev_b32_e32 v122, 16, v21
	v_pk_mul_f32 v[16:17], v[118:119], v[16:17] op_sel:[1,0] op_sel_hi:[0,1]
	global_load_dwordx4 v[52:55], v[110:111], off offset:16
	global_load_dwordx4 v[64:67], v[110:111], off
	global_load_dwordx4 v[56:59], v[48:49], off offset:16
	global_load_dwordx4 v[68:71], v[48:49], off
	s_nop 0
	global_load_dwordx4 v[48:51], v[60:61], off offset:16
	s_nop 0
	global_load_dwordx4 v[60:63], v[60:61], off
	v_lshlrev_b32_e32 v20, 16, v13
	global_load_dword v132, v[78:79], off
	v_lshlrev_b64 v[78:79], 6, v[74:75]
	v_and_b32_e32 v21, 0xffff0000, v13
	v_pk_fma_f32 v[16:17], v[118:119], v[122:123], v[16:17]
	v_lshl_add_u64 v[78:79], s[20:21], 0, v[78:79]
	v_pk_fma_f32 v[16:17], v[120:121], v[20:21], v[16:17] op_sel_hi:[0,1,1]
	v_lshlrev_b32_e32 v20, 16, v18
	v_and_b32_e32 v21, 0xffff0000, v22
	v_lshl_add_u64 v[78:79], v[78:79], 0, v[112:113]
	v_cvt_pk_bf16_f32 v13, v16, v17
	v_lshlrev_b32_e32 v16, 16, v22
	v_and_b32_e32 v17, 0xffff0000, v18
	v_pk_mul_f32 v[20:21], v[118:119], v[20:21] op_sel:[1,0] op_sel_hi:[0,1]
	v_add_co_u32_e32 v78, vcc, s41, v78
	v_lshlrev_b32_e32 v122, 16, v14
	v_and_b32_e32 v123, 0xffff0000, v14
	v_pk_fma_f32 v[16:17], v[118:119], v[16:17], v[20:21]
	v_addc_co_u32_e32 v79, vcc, 0, v79, vcc
	v_ashrrev_i32_e32 v77, 31, v76
	v_pk_fma_f32 v[16:17], v[120:121], v[122:123], v[16:17] op_sel_hi:[0,1,1]
	global_load_dword v133, v[78:79], off
	v_lshlrev_b64 v[78:79], 6, v[76:77]
	v_cvt_pk_bf16_f32 v14, v16, v17
	v_and_b32_e32 v17, 0xffff0000, v19
	v_lshlrev_b32_e32 v18, 16, v19
	v_and_b32_e32 v19, 0xffff0000, v23
	v_lshl_add_u64 v[78:79], s[20:21], 0, v[78:79]
	v_lshlrev_b32_e32 v16, 16, v23
	v_pk_mul_f32 v[18:19], v[118:119], v[18:19] op_sel:[1,0] op_sel_hi:[0,1]
	v_lshl_add_u64 v[78:79], v[78:79], 0, v[112:113]
	v_lshlrev_b64 v[72:73], 11, v[72:73]
	v_pk_fma_f32 v[16:17], v[118:119], v[16:17], v[18:19]
	v_lshlrev_b32_e32 v18, 16, v15
	v_and_b32_e32 v19, 0xffff0000, v15
	v_add_co_u32_e32 v78, vcc, s42, v78
	v_lshl_add_u64 v[114:115], v[98:99], 0, v[72:73]
	v_lshlrev_b64 v[72:73], 11, v[74:75]
	v_lshlrev_b64 v[74:75], 11, v[76:77]
	v_pk_fma_f32 v[16:17], v[120:121], v[18:19], v[16:17] op_sel_hi:[0,1,1]
	v_addc_co_u32_e32 v79, vcc, 0, v79, vcc
	v_lshl_add_u64 v[72:73], v[100:101], 0, v[72:73]
	s_waitcnt lgkmcnt(0)
	v_lshl_add_u64 v[84:85], v[102:103], 0, v[74:75]
	v_cvt_pk_bf16_f32 v15, v16, v17
	global_load_dword v134, v[78:79], off
	s_nop 0
	global_load_dwordx4 v[76:79], v[114:115], off offset:16
	global_load_dwordx4 v[88:91], v[114:115], off
	global_load_dwordx4 v[80:83], v[72:73], off offset:16
	global_load_dwordx4 v[92:95], v[72:73], off
	s_nop 0
	global_load_dwordx4 v[72:75], v[84:85], off offset:16
	s_nop 0
	global_load_dwordx4 v[84:87], v[84:85], off
	s_add_i32 s2, s33, s33
	global_store_dwordx4 v[106:107], v[12:15], off nt
	s_add_i32 s2, s2, s33
	v_add_u32_e32 v116, s97, v116
	v_lshlrev_b32_e32 v14, 16, v4
	v_and_b32_e32 v15, 0xffff0000, v8
	v_lshlrev_b32_e32 v12, 16, v8
	v_and_b32_e32 v13, 0xffff0000, v4
	v_pk_mul_f32 v[14:15], v[118:119], v[14:15] op_sel:[1,0] op_sel_hi:[0,1]
	v_pk_fma_f32 v[12:13], v[118:119], v[12:13], v[14:15]
	v_lshlrev_b32_e32 v14, 16, v0
	v_and_b32_e32 v15, 0xffff0000, v0
	v_pk_fma_f32 v[12:13], v[120:121], v[14:15], v[12:13] op_sel_hi:[0,1,1]
	v_cvt_pk_bf16_f32 v0, v12, v13
	v_and_b32_e32 v13, 0xffff0000, v5
	v_lshlrev_b32_e32 v4, 16, v5
	v_and_b32_e32 v5, 0xffff0000, v9
	v_lshlrev_b32_e32 v12, 16, v9
	v_pk_mul_f32 v[4:5], v[118:119], v[4:5] op_sel:[1,0] op_sel_hi:[0,1]
	v_pk_fma_f32 v[4:5], v[118:119], v[12:13], v[4:5]
	v_lshlrev_b32_e32 v8, 16, v1
	v_and_b32_e32 v9, 0xffff0000, v1
	v_pk_fma_f32 v[4:5], v[120:121], v[8:9], v[4:5] op_sel_hi:[0,1,1]
	v_lshlrev_b32_e32 v8, 16, v6
	v_and_b32_e32 v9, 0xffff0000, v10
	v_cvt_pk_bf16_f32 v1, v4, v5
	v_lshlrev_b32_e32 v4, 16, v10
	v_and_b32_e32 v5, 0xffff0000, v6
	v_pk_mul_f32 v[8:9], v[118:119], v[8:9] op_sel:[1,0] op_sel_hi:[0,1]
	v_pk_fma_f32 v[4:5], v[118:119], v[4:5], v[8:9]
	v_lshlrev_b32_e32 v8, 16, v2
	v_and_b32_e32 v9, 0xffff0000, v2
	v_pk_fma_f32 v[4:5], v[120:121], v[8:9], v[4:5] op_sel_hi:[0,1,1]
	v_cvt_pk_bf16_f32 v2, v4, v5
	v_and_b32_e32 v5, 0xffff0000, v7
	v_lshlrev_b32_e32 v6, 16, v7
	v_and_b32_e32 v7, 0xffff0000, v11
	v_lshlrev_b32_e32 v4, 16, v11
	v_pk_mul_f32 v[6:7], v[118:119], v[6:7] op_sel:[1,0] op_sel_hi:[0,1]
	v_pk_fma_f32 v[4:5], v[118:119], v[4:5], v[6:7]
	v_lshlrev_b32_e32 v6, 16, v3
	v_and_b32_e32 v7, 0xffff0000, v3
	v_pk_fma_f32 v[4:5], v[120:121], v[6:7], v[4:5] op_sel_hi:[0,1,1]
	v_cvt_pk_bf16_f32 v3, v4, v5
	global_store_dwordx4 v[106:107], v[0:3], off offset:16 nt
	s_waitcnt vmcnt(20)
; DI unsigned pk2(float lo, float hi) { f32x2n v = {lo, hi}; bf16x2n b = __builtin_convertvector(v, bf16x2n); return __builtin_bit_cast(unsigned, b); }
; DI float frcp(float x) { return __builtin_amdgcn_rcpf(x); }
; DI void merge_phase(bf16_t* QKV, const float* LSE, int G, int bid) {
;     ...
;         for (int r = 0; r < 4; ++r) {
;             const float m = fmaxf(l0[r], fmaxf(l1[r], l2[r])); float w0 = __expf(l0[r] - m), w1 = __expf(l1[r] - m), w2 = __expf(l2[r] - m); const float is = frcp(w0 + w1 + w2); w0 *= is; w1 *= is; w2 *= is;
; #pragma unroll
;             for (int q = 0; q < 2; ++q) { const u32x4 A = a[r][q], B = b[r][q], C = c[r][q]; u32x4 o;
;                 o.x = pk2(w0 * bflo(A.x) + w1 * bflo(B.x) + w2 * bflo(C.x), w0 * bfhi(A.x) + w1 * bfhi(B.x) + w2 * bfhi(C.x));
;                 o.y = pk2(w0 * bflo(A.y) + w1 * bflo(B.y) + w2 * bflo(C.y), w0 * bfhi(A.y) + w1 * bfhi(B.y) + w2 * bfhi(C.y));
;                 o.z = pk2(w0 * bflo(A.z) + w1 * bflo(B.z) + w2 * bflo(C.z), w0 * bfhi(A.z) + w1 * bfhi(B.z) + w2 * bfhi(C.z));
;                 o.w = pk2(w0 * bflo(A.w) + w1 * bflo(B.w) + w2 * bflo(C.w), w0 * bfhi(A.w) + w1 * bfhi(B.w) + w2 * bfhi(C.w));
;                 *(u32x4*)(p0[r] + 8 * q) = o; }
	v_lshlrev_b32_e32 v8, 16, v36
	v_and_b32_e32 v9, 0xffff0000, v36
	v_max3_f32 v2, v121, v128, v129
	v_sub_f32_e32 v0, v121, v2
	v_mul_f32_e32 v0, 0x3fb8aa3b, v0
	v_exp_f32_e32 v1, v0
	v_sub_f32_e32 v0, v128, v2
	v_mul_f32_e32 v0, 0x3fb8aa3b, v0
	v_sub_f32_e32 v2, v129, v2
	v_exp_f32_e32 v0, v0
	v_mul_f32_e32 v2, 0x3fb8aa3b, v2
	v_exp_f32_e32 v3, v2
	v_lshlrev_b32_e32 v10, 16, v37
	v_add_f32_e32 v2, v1, v0
	v_and_b32_e32 v11, 0xffff0000, v37
	v_add_f32_e32 v2, v3, v2
	v_rcp_f32_e32 v2, v2
	v_add_u32_e32 v117, s34, v117
	v_mul_f32_e32 v4, v3, v2
	v_pk_mul_f32 v[6:7], v[0:1], v[2:3] op_sel_hi:[1,0]
	v_lshlrev_b32_e32 v2, 16, v40
	v_and_b32_e32 v3, 0xffff0000, v44
	v_lshlrev_b32_e32 v0, 16, v44
	v_and_b32_e32 v1, 0xffff0000, v40
	v_pk_mul_f32 v[2:3], v[6:7], v[2:3] op_sel:[1,0] op_sel_hi:[0,1]
	v_pk_fma_f32 v[0:1], v[6:7], v[0:1], v[2:3]
	v_lshlrev_b32_e32 v2, 16, v45
	v_pk_fma_f32 v[0:1], v[4:5], v[8:9], v[0:1] op_sel_hi:[0,1,1]
	v_lshlrev_b32_e32 v8, 16, v41
	v_and_b32_e32 v9, 0xffff0000, v45
	v_and_b32_e32 v3, 0xffff0000, v41
	v_pk_mul_f32 v[8:9], v[6:7], v[8:9] op_sel:[1,0] op_sel_hi:[0,1]
	v_pk_fma_f32 v[2:3], v[6:7], v[2:3], v[8:9]
	v_lshlrev_b32_e32 v8, 16, v42
	v_pk_fma_f32 v[2:3], v[4:5], v[10:11], v[2:3] op_sel_hi:[0,1,1]
	v_and_b32_e32 v9, 0xffff0000, v46
	v_cvt_pk_bf16_f32 v0, v0, v1
	v_cvt_pk_bf16_f32 v1, v2, v3
	v_lshlrev_b32_e32 v2, 16, v46
	v_and_b32_e32 v3, 0xffff0000, v42
	v_pk_mul_f32 v[8:9], v[6:7], v[8:9] op_sel:[1,0] op_sel_hi:[0,1]
	v_lshlrev_b32_e32 v10, 16, v38
	v_and_b32_e32 v11, 0xffff0000, v38
	v_pk_fma_f32 v[2:3], v[6:7], v[2:3], v[8:9]
	v_lshlrev_b32_e32 v8, 16, v47
	v_pk_fma_f32 v[2:3], v[4:5], v[10:11], v[2:3] op_sel_hi:[0,1,1]
	v_lshlrev_b32_e32 v10, 16, v43
	v_and_b32_e32 v11, 0xffff0000, v47
	v_and_b32_e32 v9, 0xffff0000, v43
	v_pk_mul_f32 v[10:11], v[6:7], v[10:11] op_sel:[1,0] op_sel_hi:[0,1]
	v_pk_fma_f32 v[8:9], v[6:7], v[8:9], v[10:11]
	v_lshlrev_b32_e32 v10, 16, v39
	v_and_b32_e32 v11, 0xffff0000, v39
	v_pk_fma_f32 v[8:9], v[4:5], v[10:11], v[8:9] op_sel_hi:[0,1,1]
	v_cvt_pk_bf16_f32 v2, v2, v3
	v_cvt_pk_bf16_f32 v3, v8, v9
	global_store_dwordx4 v[108:109], v[0:3], off nt
	v_lshlrev_b32_e32 v8, 16, v29
	v_and_b32_e32 v9, 0xffff0000, v33
	v_lshlrev_b32_e32 v2, 16, v28
	v_and_b32_e32 v3, 0xffff0000, v32
	v_lshlrev_b32_e32 v0, 16, v32
	v_and_b32_e32 v1, 0xffff0000, v28
	v_pk_mul_f32 v[2:3], v[6:7], v[2:3] op_sel:[1,0] op_sel_hi:[0,1]
	v_pk_fma_f32 v[0:1], v[6:7], v[0:1], v[2:3]
	v_lshlrev_b32_e32 v2, 16, v24
	v_and_b32_e32 v3, 0xffff0000, v24
	v_pk_fma_f32 v[0:1], v[4:5], v[2:3], v[0:1] op_sel_hi:[0,1,1]
	v_lshlrev_b32_e32 v2, 16, v33
	v_and_b32_e32 v3, 0xffff0000, v29
	v_pk_mul_f32 v[8:9], v[6:7], v[8:9] op_sel:[1,0] op_sel_hi:[0,1]
	v_pk_fma_f32 v[2:3], v[6:7], v[2:3], v[8:9]
	v_lshlrev_b32_e32 v8, 16, v25
	v_and_b32_e32 v9, 0xffff0000, v25
	v_pk_fma_f32 v[2:3], v[4:5], v[8:9], v[2:3] op_sel_hi:[0,1,1]
	v_lshlrev_b32_e32 v8, 16, v30
	v_and_b32_e32 v9, 0xffff0000, v34
	v_cvt_pk_bf16_f32 v0, v0, v1
	v_cvt_pk_bf16_f32 v1, v2, v3
	v_lshlrev_b32_e32 v2, 16, v34
	v_and_b32_e32 v3, 0xffff0000, v30
	v_pk_mul_f32 v[8:9], v[6:7], v[8:9] op_sel:[1,0] op_sel_hi:[0,1]
	v_pk_fma_f32 v[2:3], v[6:7], v[2:3], v[8:9]
	v_lshlrev_b32_e32 v8, 16, v26
	v_and_b32_e32 v9, 0xffff0000, v26
	v_lshlrev_b32_e32 v10, 16, v31
	v_and_b32_e32 v11, 0xffff0000, v35
	v_pk_fma_f32 v[2:3], v[4:5], v[8:9], v[2:3] op_sel_hi:[0,1,1]
	v_lshlrev_b32_e32 v8, 16, v35
	v_and_b32_e32 v9, 0xffff0000, v31
	v_pk_mul_f32 v[10:11], v[6:7], v[10:11] op_sel:[1,0] op_sel_hi:[0,1]
	v_pk_fma_f32 v[6:7], v[6:7], v[8:9], v[10:11]
	v_lshlrev_b32_e32 v8, 16, v27
	v_and_b32_e32 v9, 0xffff0000, v27
	v_pk_fma_f32 v[4:5], v[4:5], v[8:9], v[6:7] op_sel_hi:[0,1,1]
	v_cvt_pk_bf16_f32 v2, v2, v3
	v_cvt_pk_bf16_f32 v3, v4, v5
	global_store_dwordx4 v[108:109], v[0:3], off offset:16 nt
	s_waitcnt vmcnt(13)
	v_lshlrev_b32_e32 v8, 16, v60
	v_and_b32_e32 v9, 0xffff0000, v60
	v_max3_f32 v2, v105, v130, v131
	v_sub_f32_e32 v0, v105, v2
	v_mul_f32_e32 v0, 0x3fb8aa3b, v0
	v_exp_f32_e32 v1, v0
	v_sub_f32_e32 v0, v130, v2
	v_mul_f32_e32 v0, 0x3fb8aa3b, v0
	v_sub_f32_e32 v2, v131, v2
	v_exp_f32_e32 v0, v0
	v_mul_f32_e32 v2, 0x3fb8aa3b, v2
	v_exp_f32_e32 v3, v2
	v_lshlrev_b32_e32 v10, 16, v61
	v_add_f32_e32 v2, v1, v0
	v_and_b32_e32 v11, 0xffff0000, v61
	v_add_f32_e32 v2, v3, v2
	v_rcp_f32_e32 v2, v2
	s_nop 0
	v_mul_f32_e32 v4, v3, v2
	v_pk_mul_f32 v[6:7], v[0:1], v[2:3] op_sel_hi:[1,0]
	v_lshlrev_b32_e32 v2, 16, v64
	v_and_b32_e32 v3, 0xffff0000, v68
	v_lshlrev_b32_e32 v0, 16, v68
	v_and_b32_e32 v1, 0xffff0000, v64
	v_pk_mul_f32 v[2:3], v[6:7], v[2:3] op_sel:[1,0] op_sel_hi:[0,1]
	v_pk_fma_f32 v[0:1], v[6:7], v[0:1], v[2:3]
	v_lshlrev_b32_e32 v2, 16, v69
	v_pk_fma_f32 v[0:1], v[4:5], v[8:9], v[0:1] op_sel_hi:[0,1,1]
	v_lshlrev_b32_e32 v8, 16, v65
	v_and_b32_e32 v9, 0xffff0000, v69
	v_and_b32_e32 v3, 0xffff0000, v65
	v_pk_mul_f32 v[8:9], v[6:7], v[8:9] op_sel:[1,0] op_sel_hi:[0,1]
	v_pk_fma_f32 v[2:3], v[6:7], v[2:3], v[8:9]
	v_lshlrev_b32_e32 v8, 16, v66
	v_pk_fma_f32 v[2:3], v[4:5], v[10:11], v[2:3] op_sel_hi:[0,1,1]
	v_and_b32_e32 v9, 0xffff0000, v70
	v_cvt_pk_bf16_f32 v0, v0, v1
	v_cvt_pk_bf16_f32 v1, v2, v3
	v_lshlrev_b32_e32 v2, 16, v70
	v_and_b32_e32 v3, 0xffff0000, v66
	v_pk_mul_f32 v[8:9], v[6:7], v[8:9] op_sel:[1,0] op_sel_hi:[0,1]
	v_lshlrev_b32_e32 v10, 16, v62
	v_and_b32_e32 v11, 0xffff0000, v62
	v_pk_fma_f32 v[2:3], v[6:7], v[2:3], v[8:9]
	v_lshlrev_b32_e32 v8, 16, v71
	v_pk_fma_f32 v[2:3], v[4:5], v[10:11], v[2:3] op_sel_hi:[0,1,1]
	v_lshlrev_b32_e32 v10, 16, v67
	v_and_b32_e32 v11, 0xffff0000, v71
	v_and_b32_e32 v9, 0xffff0000, v67
; DI unsigned pk2(float lo, float hi) { f32x2n v = {lo, hi}; bf16x2n b = __builtin_convertvector(v, bf16x2n); return __builtin_bit_cast(unsigned, b); }
; DI float frcp(float x) { return __builtin_amdgcn_rcpf(x); }
; DI void merge_phase(bf16_t* QKV, const float* LSE, int G, int bid) {
;     ...
;         for (int r = 0; r < 4; ++r) {
;             const float m = fmaxf(l0[r], fmaxf(l1[r], l2[r])); float w0 = __expf(l0[r] - m), w1 = __expf(l1[r] - m), w2 = __expf(l2[r] - m); const float is = frcp(w0 + w1 + w2); w0 *= is; w1 *= is; w2 *= is;
; #pragma unroll
;             for (int q = 0; q < 2; ++q) { const u32x4 A = a[r][q], B = b[r][q], C = c[r][q]; u32x4 o;
;                 o.x = pk2(w0 * bflo(A.x) + w1 * bflo(B.x) + w2 * bflo(C.x), w0 * bfhi(A.x) + w1 * bfhi(B.x) + w2 * bfhi(C.x));
;                 o.y = pk2(w0 * bflo(A.y) + w1 * bflo(B.y) + w2 * bflo(C.y), w0 * bfhi(A.y) + w1 * bfhi(B.y) + w2 * bfhi(C.y));
;                 o.z = pk2(w0 * bflo(A.z) + w1 * bflo(B.z) + w2 * bflo(C.z), w0 * bfhi(A.z) + w1 * bfhi(B.z) + w2 * bfhi(C.z));
;                 o.w = pk2(w0 * bflo(A.w) + w1 * bflo(B.w) + w2 * bflo(C.w), w0 * bfhi(A.w) + w1 * bfhi(B.w) + w2 * bfhi(C.w));
;                 *(u32x4*)(p0[r] + 8 * q) = o; }
	v_pk_mul_f32 v[10:11], v[6:7], v[10:11] op_sel:[1,0] op_sel_hi:[0,1]
	v_pk_fma_f32 v[8:9], v[6:7], v[8:9], v[10:11]
	v_lshlrev_b32_e32 v10, 16, v63
	v_and_b32_e32 v11, 0xffff0000, v63
	v_pk_fma_f32 v[8:9], v[4:5], v[10:11], v[8:9] op_sel_hi:[0,1,1]
	v_cvt_pk_bf16_f32 v2, v2, v3
	v_cvt_pk_bf16_f32 v3, v8, v9
	global_store_dwordx4 v[110:111], v[0:3], off nt
	v_lshlrev_b32_e32 v8, 16, v53
	v_and_b32_e32 v9, 0xffff0000, v57
	v_lshlrev_b32_e32 v2, 16, v52
	v_and_b32_e32 v3, 0xffff0000, v56
	v_lshlrev_b32_e32 v0, 16, v56
	v_and_b32_e32 v1, 0xffff0000, v52
	v_pk_mul_f32 v[2:3], v[6:7], v[2:3] op_sel:[1,0] op_sel_hi:[0,1]
	v_pk_fma_f32 v[0:1], v[6:7], v[0:1], v[2:3]
	v_lshlrev_b32_e32 v2, 16, v48
	v_and_b32_e32 v3, 0xffff0000, v48
	v_pk_fma_f32 v[0:1], v[4:5], v[2:3], v[0:1] op_sel_hi:[0,1,1]
	v_lshlrev_b32_e32 v2, 16, v57
	v_and_b32_e32 v3, 0xffff0000, v53
	v_pk_mul_f32 v[8:9], v[6:7], v[8:9] op_sel:[1,0] op_sel_hi:[0,1]
	v_pk_fma_f32 v[2:3], v[6:7], v[2:3], v[8:9]
	v_lshlrev_b32_e32 v8, 16, v49
	v_and_b32_e32 v9, 0xffff0000, v49
	v_pk_fma_f32 v[2:3], v[4:5], v[8:9], v[2:3] op_sel_hi:[0,1,1]
	v_lshlrev_b32_e32 v8, 16, v54
	v_and_b32_e32 v9, 0xffff0000, v58
	v_cvt_pk_bf16_f32 v0, v0, v1
	v_cvt_pk_bf16_f32 v1, v2, v3
	v_lshlrev_b32_e32 v2, 16, v58
	v_and_b32_e32 v3, 0xffff0000, v54
	v_pk_mul_f32 v[8:9], v[6:7], v[8:9] op_sel:[1,0] op_sel_hi:[0,1]
	v_pk_fma_f32 v[2:3], v[6:7], v[2:3], v[8:9]
	v_lshlrev_b32_e32 v8, 16, v50
	v_and_b32_e32 v9, 0xffff0000, v50
	v_lshlrev_b32_e32 v10, 16, v55
	v_and_b32_e32 v11, 0xffff0000, v59
	v_pk_fma_f32 v[2:3], v[4:5], v[8:9], v[2:3] op_sel_hi:[0,1,1]
	v_lshlrev_b32_e32 v8, 16, v59
	v_and_b32_e32 v9, 0xffff0000, v55
	v_pk_mul_f32 v[10:11], v[6:7], v[10:11] op_sel:[1,0] op_sel_hi:[0,1]
	v_pk_fma_f32 v[6:7], v[6:7], v[8:9], v[10:11]
	v_lshlrev_b32_e32 v8, 16, v51
	v_and_b32_e32 v9, 0xffff0000, v51
	v_pk_fma_f32 v[4:5], v[4:5], v[8:9], v[6:7] op_sel_hi:[0,1,1]
	v_cvt_pk_bf16_f32 v2, v2, v3
	v_cvt_pk_bf16_f32 v3, v4, v5
	global_store_dwordx4 v[110:111], v[0:3], off offset:16 nt
	s_waitcnt vmcnt(6)
	v_lshlrev_b32_e32 v8, 16, v84
	v_and_b32_e32 v9, 0xffff0000, v84
	v_max3_f32 v2, v132, v133, v134
	v_sub_f32_e32 v0, v132, v2
	v_mul_f32_e32 v0, 0x3fb8aa3b, v0
	v_exp_f32_e32 v1, v0
	v_sub_f32_e32 v0, v133, v2
	v_mul_f32_e32 v0, 0x3fb8aa3b, v0
	v_sub_f32_e32 v2, v134, v2
	v_exp_f32_e32 v0, v0
	v_mul_f32_e32 v2, 0x3fb8aa3b, v2
	v_exp_f32_e32 v3, v2
	v_lshlrev_b32_e32 v10, 16, v85
	v_add_f32_e32 v2, v1, v0
	v_and_b32_e32 v11, 0xffff0000, v85
	v_add_f32_e32 v2, v3, v2
	v_rcp_f32_e32 v2, v2
	s_nop 0
	v_mul_f32_e32 v4, v3, v2
	v_pk_mul_f32 v[6:7], v[0:1], v[2:3] op_sel_hi:[1,0]
	v_lshlrev_b32_e32 v2, 16, v88
	v_and_b32_e32 v3, 0xffff0000, v92
	v_lshlrev_b32_e32 v0, 16, v92
	v_and_b32_e32 v1, 0xffff0000, v88
	v_pk_mul_f32 v[2:3], v[6:7], v[2:3] op_sel:[1,0] op_sel_hi:[0,1]
	v_pk_fma_f32 v[0:1], v[6:7], v[0:1], v[2:3]
	v_lshlrev_b32_e32 v2, 16, v93
	v_pk_fma_f32 v[0:1], v[4:5], v[8:9], v[0:1] op_sel_hi:[0,1,1]
	v_lshlrev_b32_e32 v8, 16, v89
	v_and_b32_e32 v9, 0xffff0000, v93
	v_and_b32_e32 v3, 0xffff0000, v89
	v_pk_mul_f32 v[8:9], v[6:7], v[8:9] op_sel:[1,0] op_sel_hi:[0,1]
	v_pk_fma_f32 v[2:3], v[6:7], v[2:3], v[8:9]
	v_lshlrev_b32_e32 v8, 16, v90
	v_pk_fma_f32 v[2:3], v[4:5], v[10:11], v[2:3] op_sel_hi:[0,1,1]
	v_and_b32_e32 v9, 0xffff0000, v94
	v_cvt_pk_bf16_f32 v0, v0, v1
	v_cvt_pk_bf16_f32 v1, v2, v3
	v_lshlrev_b32_e32 v2, 16, v94
	v_and_b32_e32 v3, 0xffff0000, v90
	v_pk_mul_f32 v[8:9], v[6:7], v[8:9] op_sel:[1,0] op_sel_hi:[0,1]
	v_lshlrev_b32_e32 v10, 16, v86
	v_and_b32_e32 v11, 0xffff0000, v86
	v_pk_fma_f32 v[2:3], v[6:7], v[2:3], v[8:9]
	v_lshlrev_b32_e32 v8, 16, v95
	v_pk_fma_f32 v[2:3], v[4:5], v[10:11], v[2:3] op_sel_hi:[0,1,1]
	v_lshlrev_b32_e32 v10, 16, v91
	v_and_b32_e32 v11, 0xffff0000, v95
	v_and_b32_e32 v9, 0xffff0000, v91
	v_pk_mul_f32 v[10:11], v[6:7], v[10:11] op_sel:[1,0] op_sel_hi:[0,1]
	v_pk_fma_f32 v[8:9], v[6:7], v[8:9], v[10:11]
	v_lshlrev_b32_e32 v10, 16, v87
	v_and_b32_e32 v11, 0xffff0000, v87
	v_pk_fma_f32 v[8:9], v[4:5], v[10:11], v[8:9] op_sel_hi:[0,1,1]
	v_cvt_pk_bf16_f32 v2, v2, v3
	v_cvt_pk_bf16_f32 v3, v8, v9
	global_store_dwordx4 v[114:115], v[0:3], off nt
	v_lshlrev_b32_e32 v8, 16, v77
	v_and_b32_e32 v9, 0xffff0000, v81
	v_lshlrev_b32_e32 v2, 16, v76
	v_and_b32_e32 v3, 0xffff0000, v80
	v_lshlrev_b32_e32 v0, 16, v80
	v_and_b32_e32 v1, 0xffff0000, v76
	v_pk_mul_f32 v[2:3], v[6:7], v[2:3] op_sel:[1,0] op_sel_hi:[0,1]
	v_pk_fma_f32 v[0:1], v[6:7], v[0:1], v[2:3]
	v_lshlrev_b32_e32 v2, 16, v72
	v_and_b32_e32 v3, 0xffff0000, v72
	v_pk_fma_f32 v[0:1], v[4:5], v[2:3], v[0:1] op_sel_hi:[0,1,1]
	v_lshlrev_b32_e32 v2, 16, v81
	v_and_b32_e32 v3, 0xffff0000, v77
	v_pk_mul_f32 v[8:9], v[6:7], v[8:9] op_sel:[1,0] op_sel_hi:[0,1]
	v_pk_fma_f32 v[2:3], v[6:7], v[2:3], v[8:9]
	v_lshlrev_b32_e32 v8, 16, v73
	v_and_b32_e32 v9, 0xffff0000, v73
	v_pk_fma_f32 v[2:3], v[4:5], v[8:9], v[2:3] op_sel_hi:[0,1,1]
	v_lshlrev_b32_e32 v8, 16, v78
	v_and_b32_e32 v9, 0xffff0000, v82
	v_cvt_pk_bf16_f32 v0, v0, v1
	v_cvt_pk_bf16_f32 v1, v2, v3
	v_lshlrev_b32_e32 v2, 16, v82
	v_and_b32_e32 v3, 0xffff0000, v78
	v_pk_mul_f32 v[8:9], v[6:7], v[8:9] op_sel:[1,0] op_sel_hi:[0,1]
	v_pk_fma_f32 v[2:3], v[6:7], v[2:3], v[8:9]
	v_lshlrev_b32_e32 v8, 16, v74
	v_and_b32_e32 v9, 0xffff0000, v74
	v_lshlrev_b32_e32 v10, 16, v79
	v_and_b32_e32 v11, 0xffff0000, v83
	v_pk_fma_f32 v[2:3], v[4:5], v[8:9], v[2:3] op_sel_hi:[0,1,1]
	v_lshlrev_b32_e32 v8, 16, v83
	v_and_b32_e32 v9, 0xffff0000, v79
	v_pk_mul_f32 v[10:11], v[6:7], v[10:11] op_sel:[1,0] op_sel_hi:[0,1]
	v_pk_fma_f32 v[6:7], v[6:7], v[8:9], v[10:11]
	v_lshlrev_b32_e32 v8, 16, v75
	v_and_b32_e32 v9, 0xffff0000, v75
	v_add_u32_e32 v72, s2, v104
	s_movk_i32 s2, 0x3fff
	v_pk_fma_f32 v[4:5], v[4:5], v[8:9], v[6:7] op_sel_hi:[0,1,1]
	v_cmp_lt_i32_e32 vcc, s2, v72
	v_cvt_pk_bf16_f32 v2, v2, v3
	v_cvt_pk_bf16_f32 v3, v4, v5
	s_or_b64 s[38:39], vcc, s[38:39]
	global_store_dwordx4 v[114:115], v[0:3], off offset:16 nt
	s_andn2_b64 exec, exec, s[38:39]
	s_cbranch_execnz .LBB0_308
